# hazard hardening: MFMA(8-pass)-result-to-VALU read distance padded to >=12 wait states in the NSA selected/window fast paths (s_nop), otherwise identical to v_m28
# speedup vs baseline: 1.0001x; 1.0001x over previous
.LBB0_407:
	s_nop 4
	v_exp_f32_e32 v18, v18
	v_exp_f32_e32 v2, v2
	v_exp_f32_e32 v19, v19
	v_exp_f32_e32 v3, v3
	v_add_f32_e32 v177, v18, v2
	v_exp_f32_e32 v20, v20
	v_exp_f32_e32 v4, v4
	v_add_f32_e32 v176, v19, v3
	v_add_f32_e32 v177, v176, v177
	v_exp_f32_e32 v21, v21
	v_exp_f32_e32 v5, v5
	v_add_f32_e32 v176, v20, v4
	v_add_f32_e32 v177, v176, v177
	v_exp_f32_e32 v22, v22
	v_exp_f32_e32 v6, v6
	v_add_f32_e32 v176, v21, v5
	v_add_f32_e32 v177, v176, v177
	v_exp_f32_e32 v23, v23
	v_exp_f32_e32 v7, v7
	v_add_f32_e32 v176, v22, v6
	v_add_f32_e32 v177, v176, v177
	v_exp_f32_e32 v24, v24
	v_exp_f32_e32 v8, v8
	v_add_f32_e32 v176, v23, v7
	v_add_f32_e32 v177, v176, v177
	v_exp_f32_e32 v25, v25
	v_exp_f32_e32 v9, v9
	v_add_f32_e32 v176, v24, v8
	v_add_f32_e32 v177, v176, v177
	v_exp_f32_e32 v26, v26
	v_exp_f32_e32 v10, v10
	v_add_f32_e32 v176, v25, v9
	v_add_f32_e32 v177, v176, v177
	v_exp_f32_e32 v27, v27
	v_exp_f32_e32 v11, v11
	v_add_f32_e32 v176, v26, v10
	v_add_f32_e32 v177, v176, v177
	v_exp_f32_e32 v28, v28
	v_exp_f32_e32 v12, v12
	v_add_f32_e32 v176, v27, v11
	v_add_f32_e32 v177, v176, v177
	v_exp_f32_e32 v29, v29
	v_exp_f32_e32 v13, v13
	v_add_f32_e32 v176, v28, v12
	v_add_f32_e32 v177, v176, v177
	v_exp_f32_e32 v30, v30
	v_exp_f32_e32 v14, v14
	v_add_f32_e32 v176, v29, v13
	v_add_f32_e32 v177, v176, v177
	v_exp_f32_e32 v31, v31
	v_exp_f32_e32 v15, v15
	v_add_f32_e32 v176, v30, v14
	v_add_f32_e32 v177, v176, v177
	v_exp_f32_e32 v32, v32
	v_exp_f32_e32 v16, v16
	v_add_f32_e32 v176, v31, v15
	v_add_f32_e32 v177, v176, v177
	v_exp_f32_e32 v33, v33
	v_exp_f32_e32 v17, v17
	v_add_f32_e32 v176, v32, v16
	v_add_f32_e32 v177, v176, v177
	v_add_f32_e32 v176, v33, v17
	v_add_f32_e32 v177, v176, v177
	v_cmp_lt_f32_e32 vcc, 0x47800000, v177
	s_cbranch_vccnz .Lmy_rd_s

.LBB0_418:
	s_nop 2
	v_exp_f32_e32 v114, v114
	v_exp_f32_e32 v98, v98
	v_exp_f32_e32 v115, v115
	v_exp_f32_e32 v99, v99
	v_add_f32_e32 v196, v114, v98
	v_exp_f32_e32 v116, v116
	v_exp_f32_e32 v100, v100
	v_add_f32_e32 v195, v115, v99
	v_add_f32_e32 v196, v195, v196
	v_exp_f32_e32 v117, v117
	v_exp_f32_e32 v101, v101
	v_add_f32_e32 v195, v116, v100
	v_add_f32_e32 v196, v195, v196
	v_exp_f32_e32 v118, v118
	v_exp_f32_e32 v102, v102
	v_add_f32_e32 v195, v117, v101
	v_add_f32_e32 v196, v195, v196
	v_exp_f32_e32 v119, v119
	v_exp_f32_e32 v103, v103
	v_add_f32_e32 v195, v118, v102
	v_add_f32_e32 v196, v195, v196
	v_exp_f32_e32 v120, v120
	v_exp_f32_e32 v104, v104
	v_add_f32_e32 v195, v119, v103
	v_add_f32_e32 v196, v195, v196
	v_exp_f32_e32 v121, v121
	v_exp_f32_e32 v105, v105
	v_add_f32_e32 v195, v120, v104
	v_add_f32_e32 v196, v195, v196
	v_exp_f32_e32 v122, v122
	v_exp_f32_e32 v106, v106
	v_add_f32_e32 v195, v121, v105
	v_add_f32_e32 v196, v195, v196
	v_exp_f32_e32 v123, v123
	v_exp_f32_e32 v107, v107
	v_add_f32_e32 v195, v122, v106
	v_add_f32_e32 v196, v195, v196
	v_exp_f32_e32 v124, v124
	v_exp_f32_e32 v108, v108
	v_add_f32_e32 v195, v123, v107
	v_add_f32_e32 v196, v195, v196
	v_exp_f32_e32 v125, v125
	v_exp_f32_e32 v109, v109
	v_add_f32_e32 v195, v124, v108
	v_add_f32_e32 v196, v195, v196
	v_exp_f32_e32 v126, v126
	v_exp_f32_e32 v110, v110
	v_add_f32_e32 v195, v125, v109
	v_add_f32_e32 v196, v195, v196
	v_exp_f32_e32 v127, v127
	v_exp_f32_e32 v111, v111
	v_add_f32_e32 v195, v126, v110
	v_add_f32_e32 v196, v195, v196
	v_exp_f32_e32 v128, v128
	v_exp_f32_e32 v112, v112
	v_add_f32_e32 v195, v127, v111
	v_add_f32_e32 v196, v195, v196
	v_exp_f32_e32 v129, v129
	v_exp_f32_e32 v113, v113
	v_add_f32_e32 v195, v128, v112
	v_add_f32_e32 v196, v195, v196
	v_add_f32_e32 v195, v129, v113
	v_add_f32_e32 v196, v195, v196
	v_cmp_lt_f32_e32 vcc, 0x47800000, v196
	s_cbranch_vccnz .Lmy_rd_w
